# adds: attention unit header issues the 8th Q fragment load with the other seven (one dependent round trip less per unit)
# baseline (speedup 1.0000x reference)
; #define LAS __attribute__((address_space(3)))
; __device__ __forceinline__ void attn_phase(LAS unsigned char* lds, const bf16_t* Qb, const bf16_t* Kb, const bf16_t* VT, bf16_t* MIX,
;                                            const float* tblg, const float* ga) {
;     ...
;     for (int ui = 0, unit = blockIdx.x; unit < NB * 32; unit += gridDim.x, ++ui) {
;         const int b = xmap ? (int)(blockIdx.x & 7) + 8 * ui : unit >> 5, r = xmap ? (int)(blockIdx.x >> 3) : unit & 31;
;         const int r0 = min(max(r - 4, 0), 24);
;         LAS bf16x8* qlds = (LAS bf16x8*)(lds + 69632 + h * 8192);
;         {
;             const bf16_t* qbase = Qb + (((size_t)(b * 32 + r) * 8 + h) * 8) * 512 + lane * 8;
; #pragma unroll
;             for (int qt = 0; qt < 4; ++qt)
; #pragma unroll
;                 for (int ks = 0; ks < 2; ++ks) qlds[(qt * 2 + ks) * 64 + lane] = *(const bf16x8*)(qbase + (qt * 2 + ks) * 512);
;         }
;         f32x4 O[4][4]; float l[4];
; #pragma unroll
;         for (int qt = 0; qt < 4; ++qt) { l[qt] = 0.f;
; #pragma unroll
;             for (int nt = 0; nt < 4; ++nt) O[qt][nt] = (f32x4){0.f, 0.f, 0.f, 0.f}; }
.LBB0_648:
	s_lshl_b32 s6, s8, 3
	v_readlane_b32 s7, v254, 20
	s_or_b32 s16, s6, s7
	s_ashr_i32 s17, s9, 5
	s_and_b64 s[6:7], s[94:95], exec
	s_cselect_b32 s16, s16, s17
	s_and_b32 s17, s9, 31
	s_and_b64 s[6:7], s[94:95], exec
	v_readlane_b32 s6, v254, 21
	s_cselect_b32 s17, s6, s17
	s_max_i32 s6, s17, 4
	s_lshl_b32 s21, s16, 5
	s_add_i32 s20, s6, -4
	s_add_i32 s6, s21, s17
	s_ashr_i32 s7, s6, 31
	s_lshl_b64 s[6:7], s[6:7], 16
	v_lshl_add_u64 v[0:1], v[164:165], 0, s[6:7]
	v_add_co_u32_e64 v4, s[42:43], s72, v0
	global_load_dwordx4 v[8:11], v[0:1], off
	global_load_dwordx4 v[12:15], v[0:1], off offset:1024
	v_addc_co_u32_e64 v5, s[42:43], 0, v1, s[42:43]
	global_load_dwordx4 v[16:19], v[0:1], off offset:2048
	global_load_dwordx4 v[20:23], v[0:1], off offset:3072
	global_load_dwordx4 v[24:27], v[4:5], off
	global_load_dwordx4 v[28:31], v[4:5], off offset:1024
	s_min_u32 s22, s20, 24
	global_load_dwordx4 v[0:3], v[4:5], off offset:2048
	global_load_dwordx4 v[32:35], v[4:5], off offset:3072
	s_or_b32 s6, s22, s21
	s_ashr_i32 s7, s6, 31
	s_lshl_b64 s[20:21], s[6:7], 15
	s_add_u32 s20, s20, s4
	s_addc_u32 s21, s21, s5
	s_lshl_b64 s[20:21], s[20:21], 1
	v_lshl_add_u64 v[178:179], v[166:167], 0, s[20:21]
	v_lshl_add_u64 v[180:181], v[168:169], 0, s[20:21]
	s_lshl_b32 s20, s22, 9
	s_lshl_b32 s21, s17, 9
	s_sub_i32 s20, s20, s21
	s_lshl_b64 s[6:7], s[6:7], 16
	v_mov_b32_e32 v212, 0
	v_mov_b64_e32 v[238:239], 0x400
	v_add_u32_e32 v214, s20, v192
	v_lshl_add_u64 v[182:183], v[174:175], 0, s[6:7]
	v_lshl_add_u64 v[184:185], v[176:177], 0, s[6:7]
	s_mov_b64 s[6:7], 0
	s_mov_b32 s20, 0x8000
	v_mov_b32_e32 v213, 0
	v_mov_b32_e32 v215, 0
	v_mov_b32_e32 v216, 0
	v_mov_b64_e32 v[186:187], v[178:179]
	v_mov_b64_e32 v[160:161], v[180:181]
	v_mov_b32_e32 v52, 0
	v_mov_b32_e32 v53, v212
	v_mov_b32_e32 v54, v212
	v_mov_b32_e32 v55, v212
	v_mov_b32_e32 v64, 0
	v_mov_b32_e32 v65, v212
	v_mov_b32_e32 v66, v212
	v_mov_b32_e32 v67, v212
	v_mov_b32_e32 v56, 0
	v_mov_b32_e32 v57, v212
	v_mov_b32_e32 v58, v212
	v_mov_b32_e32 v59, v212
	v_mov_b32_e32 v60, 0
	v_mov_b32_e32 v61, v212
	v_mov_b32_e32 v62, v212
	v_mov_b32_e32 v63, v212
	v_mov_b32_e32 v84, 0
	v_mov_b32_e32 v85, v212
	v_mov_b32_e32 v86, v212
	v_mov_b32_e32 v87, v212
	v_mov_b32_e32 v76, 0
	v_mov_b32_e32 v77, v212
	v_mov_b32_e32 v78, v212
	v_mov_b32_e32 v79, v212
	v_mov_b32_e32 v68, 0
	v_mov_b32_e32 v69, v212
	v_mov_b32_e32 v70, v212
	v_mov_b32_e32 v71, v212
	v_mov_b32_e32 v72, 0
	v_mov_b32_e32 v73, v212
	v_mov_b32_e32 v74, v212
	v_mov_b32_e32 v75, v212
	v_mov_b32_e32 v96, 0
	v_mov_b32_e32 v97, v212
	v_mov_b32_e32 v98, v212
	v_mov_b32_e32 v99, v212
	v_mov_b32_e32 v92, 0
	v_mov_b32_e32 v93, v212
	v_mov_b32_e32 v94, v212
	v_mov_b32_e32 v95, v212
	v_mov_b32_e32 v88, 0
	v_mov_b32_e32 v89, v212
	v_mov_b32_e32 v90, v212
	v_mov_b32_e32 v91, v212
	v_mov_b32_e32 v80, 0
	v_mov_b32_e32 v81, v212
	s_waitcnt vmcnt(7)
	ds_write_b128 v190, v[8:11]
	s_waitcnt vmcnt(6)
	ds_write_b128 v190, v[12:15] offset:1024
	v_mov_b32_e32 v82, v212
	v_mov_b32_e32 v83, v212
	s_waitcnt vmcnt(5)
	ds_write_b128 v190, v[16:19] offset:2048
	s_waitcnt vmcnt(4)
	ds_write_b128 v190, v[20:23] offset:3072
	s_waitcnt vmcnt(3)
	ds_write_b128 v190, v[24:27] offset:4096
	s_waitcnt vmcnt(2)
	ds_write_b128 v190, v[28:31] offset:5120
	v_mov_b32_e32 v48, 0
	s_waitcnt vmcnt(1)
	ds_write_b128 v190, v[0:3] offset:6144
	v_mov_b32_e32 v49, v212
	v_mov_b32_e32 v50, v212
	v_mov_b32_e32 v51, v212
	v_mov_b32_e32 v44, 0
	v_mov_b32_e32 v45, v212
	v_mov_b32_e32 v46, v212
	v_mov_b32_e32 v47, v212
	v_mov_b32_e32 v4, 0
	v_mov_b32_e32 v5, v212
	v_mov_b32_e32 v6, v212
	v_mov_b32_e32 v7, v212
	s_waitcnt vmcnt(0)
	ds_write_b128 v190, v[32:35] offset:7168
	ds_read_b128 v[32:35], v191 offset:63488
	ds_read_b128 v[36:39], v191 offset:64512
	ds_read_b128 v[40:43], v207 offset:3072
	v_mov_b32_e32 v0, 0
	v_mov_b32_e32 v1, v212
	v_mov_b32_e32 v2, v212
	v_mov_b32_e32 v3, v212
